# proj GEMM: removed the full vmcnt(0) drain in the tile preheader (epilogue stores no longer waited before the next K-loop)
# speedup vs baseline: 1.0085x; 1.0055x over previous
;     DEV bool next(int i, Unit& u) const { return tile((long)i * G + c, u); }
;     DEV bool next(int i, Unit& u) const { const int round = i / 3, br = i - round * 3; Unit t; if (!so.tile((long)round * so.G + so.c, t)) return false; u.pm = br * 64 + t.pm; u.pn = br * 4 + t.pn; return true; }
; template <bool ALIGN_EPI, class Epi, class Sched>
; DEV void gemm_phase(LAS unsigned char* lds, const Gemm g, const Sched& S, const Epi& E) {
;     ...
;         const bool has_next = S.next(ui + 1, nxt);
;         const char* nA = has_next ? (const char*)g.A + (size_t)nxt.pm * tstep : cA; const char* nB = has_next ? (const char*)g.Bt + (size_t)nxt.pn * tstep : cB;
;     ...
;         if (rst) {
; #pragma unroll
;         for (int a = 0; a < 2; ++a)
; #pragma unroll
;             for (int b = 0; b < 2; ++b)
; #pragma unroll
;                 for (int m = 0; m < 4; ++m)
; #pragma unroll
;                     for (int n = 0; n < 2; ++n) acc[a][b][m][n] = (f32x4){0.f, 0.f, 0.f, 0.f}; }
;         cur = nxt; cA = nA; cB = nB; ++ui;
.LBB0_314:
	s_ashr_i32 s93, s92, 31
	s_lshl_b64 s[46:47], s[92:93], 19
	s_add_u32 s88, s34, s46
	s_addc_u32 s89, s35, s47
	s_and_b64 s[46:47], s[44:45], exec
	s_cselect_b32 s17, s89, s5
	s_cselect_b32 s36, s88, s4
	s_ashr_i32 s85, s84, 31
	s_lshl_b64 s[46:47], s[84:85], 19
	s_add_u32 s90, s62, s46
	s_addc_u32 s91, s63, s47
	s_and_b64 s[46:47], s[44:45], exec
	s_cselect_b32 s41, s91, s7
	s_cselect_b32 s64, s90, s6
	s_add_u32 s70, s6, 0x100
	v_mov_b32_e32 v2, 0
	s_addc_u32 s85, s7, 0
	s_mov_b32 s87, -2
	v_mov_b32_e32 v3, v2
	v_mov_b64_e32 v[4:5], 0
	v_mov_b64_e32 v[6:7], 0
	v_mov_b64_e32 v[8:9], 0
	v_mov_b64_e32 v[18:19], 0
	v_mov_b64_e32 v[20:21], 0
	v_mov_b64_e32 v[22:23], 0
	v_mov_b64_e32 v[24:25], 0
	v_mov_b64_e32 v[34:35], 0
	v_mov_b64_e32 v[36:37], 0
	v_mov_b64_e32 v[38:39], 0
	v_mov_b64_e32 v[40:41], 0
	v_mov_b64_e32 v[50:51], 0
	v_mov_b64_e32 v[52:53], 0
	v_mov_b64_e32 v[54:55], 0
	v_mov_b64_e32 v[56:57], 0
	v_mov_b64_e32 v[10:11], 0
	v_mov_b64_e32 v[12:13], 0
	v_mov_b64_e32 v[14:15], 0
	v_mov_b64_e32 v[16:17], 0
	v_mov_b64_e32 v[26:27], 0
	v_mov_b64_e32 v[28:29], 0
	v_mov_b64_e32 v[30:31], 0
	v_mov_b64_e32 v[32:33], 0
	v_mov_b64_e32 v[42:43], 0
	v_mov_b64_e32 v[44:45], 0
	v_mov_b64_e32 v[46:47], 0
	v_mov_b64_e32 v[48:49], 0
	v_mov_b64_e32 v[58:59], 0
	v_mov_b64_e32 v[60:61], 0
	v_mov_b64_e32 v[62:63], 0
	v_mov_b64_e32 v[64:65], 0
	v_mov_b64_e32 v[66:67], 0
	v_mov_b64_e32 v[68:69], 0
	v_mov_b64_e32 v[70:71], 0
	v_mov_b64_e32 v[72:73], 0
	v_mov_b64_e32 v[82:83], 0
	v_mov_b64_e32 v[84:85], 0
	v_mov_b64_e32 v[86:87], 0
	v_mov_b64_e32 v[88:89], 0
	v_mov_b64_e32 v[98:99], 0
	v_mov_b64_e32 v[100:101], 0
	v_mov_b64_e32 v[102:103], 0
	v_mov_b64_e32 v[104:105], 0
	v_mov_b64_e32 v[114:115], 0
	v_mov_b64_e32 v[116:117], 0
	v_mov_b64_e32 v[118:119], 0
	v_mov_b64_e32 v[120:121], 0
	v_mov_b64_e32 v[74:75], 0
	v_mov_b64_e32 v[76:77], 0
	v_mov_b64_e32 v[78:79], 0
	v_mov_b64_e32 v[80:81], 0
	v_mov_b64_e32 v[90:91], 0
	v_mov_b64_e32 v[92:93], 0
	v_mov_b64_e32 v[94:95], 0
	v_mov_b64_e32 v[96:97], 0
	v_mov_b64_e32 v[106:107], 0
	v_mov_b64_e32 v[108:109], 0
	v_mov_b64_e32 v[110:111], 0
	v_mov_b64_e32 v[112:113], 0
	v_mov_b64_e32 v[122:123], 0
	v_mov_b64_e32 v[124:125], 0
	v_mov_b64_e32 v[126:127], 0
	v_mov_b64_e32 v[128:129], 0
